# S5 first pass: 17 loop-invariant LDS address adds hoisted out of the block loop
# baseline (speedup 1.0000x reference)
; __device__ __forceinline__ void s5_phase(LAS unsigned char* lds, const bf16_t* USSM, const float* S5A, const float* S5B, const float* c_re, const float* c_im, const float* dskip,
;                                          bf16_t* YSSM, int tid, int lane, int wave) {
;     ...
;         const float are = S5A[(g * 64 + lane) * 2], aim = S5A[(g * 64 + lane) * 2 + 1];
;         bf16x8 bfr[8], cfr[4];
; #pragma unroll
;         for (int nt = 0; nt < 8; ++nt) { const int pp = nt * 16 + r16, p = pp & 63, im = pp >> 6; bfr[nt] = q4 < 2 ? pack_bf8(S5B + (size_t)(g * 64 + p) * 32 + im * 16 + q4 * 8, 1.f) : zf; }
; #pragma unroll
;         for (int ks = 0; ks < 4; ++ks) { const int pp = ks * 32 + q4 * 8, p = pp & 63, im = pp >> 6; cfr[ks] = pack_bf8((im ? c_im : c_re) + (size_t)(g * 16 + r16) * 64 + p, im ? -1.f : 1.f); }
;         const float dsk = dskip[g * 16 + r16];
;         const bf16_t* ub = USSM + ((size_t)(b * SEQ + wave * 1024)) * 1024 + g * 16;
;         float xr = 0.f, xi = 0.f;
;         for (int tb = 0; tb < 64; ++tb) {
;             bf16x8 a = *(const bf16x8*)(ub + (size_t)(tb * 16 + r16) * 1024 + (q4 & 1) * 8); if (q4 >= 2) a = zf;
.LBB0_584:
	s_or_b64 exec, exec, s[14:15]
	v_lshl_or_b32 v82, s6, 12, v117
	v_lshl_add_u64 v[40:41], v[88:89], 0, v[82:83]
	global_load_dwordx4 v[32:35], v[40:41], off
	global_load_dwordx4 v[36:39], v[40:41], off offset:16
	v_lshl_add_u64 v[50:51], v[90:91], 0, v[82:83]
	s_lshl_b32 s6, s6, 4
	v_or_b32_e32 v49, s6, v81
	v_lshlrev_b32_e32 v49, 2, v49
	s_and_b32 s14, s27, 0xffffe000
	s_add_i32 s46, s3, s14
	s_ashr_i32 s47, s46, 31
	s_and_b32 s12, s42, 63
	s_lshl_b64 s[46:47], s[46:47], 11
	s_lshl_b32 s12, s12, 5
	s_or_b32 s46, s46, s12
	v_lshl_add_u64 v[96:97], v[92:93], 0, s[46:47]
	s_waitcnt vmcnt(2)
	v_pk_mov_b32 v[98:99], v[94:95], v[94:95] op_sel:[1,0]
	s_mov_b64 s[58:59], 0
	s_waitcnt vmcnt(1)
	v_cvt_pk_bf16_f32 v32, v32, v33
	v_cvt_pk_bf16_f32 v33, v34, v35
	s_waitcnt vmcnt(0)
	v_cvt_pk_bf16_f32 v34, v36, v37
	v_cvt_pk_bf16_f32 v35, v38, v39
	global_load_dwordx4 v[36:39], v[40:41], off offset:128
	s_nop 0
	global_load_dwordx4 v[40:43], v[40:41], off offset:144
	s_waitcnt vmcnt(1)
	v_cvt_pk_bf16_f32 v36, v36, v37
	v_cvt_pk_bf16_f32 v37, v38, v39
	s_waitcnt vmcnt(0)
	v_cvt_pk_bf16_f32 v38, v40, v41
	v_cvt_pk_bf16_f32 v39, v42, v43
	global_load_dwordx4 v[40:43], v[50:51], off
	global_load_dwordx4 v[44:47], v[50:51], off offset:16
	s_waitcnt vmcnt(1)
	v_xor_b32_e32 v40, 0x80000000, v40
	v_xor_b32_e32 v41, 0x80000000, v41
	v_xor_b32_e32 v42, 0x80000000, v42
	v_xor_b32_e32 v43, 0x80000000, v43
	s_waitcnt vmcnt(0)
	v_xor_b32_e32 v44, 0x80000000, v44
	v_xor_b32_e32 v45, 0x80000000, v45
	v_xor_b32_e32 v46, 0x80000000, v46
	v_xor_b32_e32 v47, 0x80000000, v47
	v_cvt_pk_bf16_f32 v40, v40, v41
	v_cvt_pk_bf16_f32 v41, v42, v43
	v_cvt_pk_bf16_f32 v42, v44, v45
	v_cvt_pk_bf16_f32 v43, v46, v47
	global_load_dwordx4 v[44:47], v[50:51], off offset:128
	s_nop 0
	global_load_dwordx4 v[50:53], v[50:51], off offset:144
	s_waitcnt vmcnt(1)
	v_xor_b32_e32 v44, 0x80000000, v44
	v_xor_b32_e32 v45, 0x80000000, v45
	v_xor_b32_e32 v46, 0x80000000, v46
	v_xor_b32_e32 v47, 0x80000000, v47
	s_waitcnt vmcnt(0)
	v_xor_b32_e32 v50, 0x80000000, v50
	v_xor_b32_e32 v51, 0x80000000, v51
	v_xor_b32_e32 v52, 0x80000000, v52
	v_xor_b32_e32 v53, 0x80000000, v53
	v_cvt_pk_bf16_f32 v44, v44, v45
	v_cvt_pk_bf16_f32 v45, v46, v47
	v_cvt_pk_bf16_f32 v46, v50, v51
	v_cvt_pk_bf16_f32 v47, v52, v53
	global_load_dword v123, v49, s[82:83]
	v_mov_b32_e32 v49, v48
	v_add_u32_e32 v124, 0x1000, v122
	v_add_u32_e32 v125, 0x1400, v122
	v_add_u32_e32 v126, 16, v111
	v_add_u32_e32 v127, 32, v111
	v_add_u32_e32 v128, 48, v111
	v_add_u32_e32 v129, 64, v111
	v_add_u32_e32 v130, 0x50, v111
	v_add_u32_e32 v131, 0x60, v111
	v_add_u32_e32 v132, 0x70, v111
	v_add_u32_e32 v133, 0x80, v111
	v_add_u32_e32 v134, 0x90, v111
	v_add_u32_e32 v135, 0xa0, v111
	v_add_u32_e32 v136, 0xb0, v111
	v_add_u32_e32 v137, 0xc0, v111
	v_add_u32_e32 v138, 0xd0, v111
	v_add_u32_e32 v139, 0xe0, v111
	v_add_u32_e32 v140, 0xf0, v111
	v_lshl_add_u64 v[156:157], v[96:97], 0, s[58:59]
	global_load_dwordx4 v[148:151], v[156:157], off
; #define LDS_WAIT() asm volatile("s_waitcnt lgkmcnt(0)" ::: "memory")
; #define MFMA16(a, b, c) __builtin_amdgcn_mfma_f32_16x16x32_bf16(a, b, c, 0, 0, 0)
; __device__ __forceinline__ void s5_phase(LAS unsigned char* lds, const bf16_t* USSM, const float* S5A, const float* S5B, const float* c_re, const float* c_im, const float* dskip,
;                                          bf16_t* YSSM, int tid, int lane, int wave) {
;     ...
;         for (int tb = 0; tb < 64; ++tb) {
;             bf16x8 a = *(const bf16x8*)(ub + (size_t)(tb * 16 + r16) * 1024 + (q4 & 1) * 8); if (q4 >= 2) a = zf;
; #pragma unroll
;             for (int nt = 0; nt < 8; ++nt) { const f32x4 acc = MFMA16(a, bfr[nt], z4);
; #pragma unroll
;                 for (int i = 0; i < 4; ++i) BU[(q4 * 4 + i) * 132 + nt * 16 + r16] = acc[i]; }
;             LDS_WAIT();
; #pragma unroll
;             for (int t = 0; t < 16; ++t) { const float br = BU[t * 132 + lane], bi = BU[t * 132 + 64 + lane];
;                 const float nr = are * xr - aim * xi + br, ni = are * xi + aim * xr + bi; xr = nr; xi = ni; }
;             LDS_WAIT();
;         }
;         carry[(wave * 64 + lane) * 2] = xr; carry[(wave * 64 + lane) * 2 + 1] = xi;
;         __syncthreads();
;         float pr = are, pi = aim;
; #pragma unroll
;         for (int k = 0; k < 10; ++k) { const float t2 = pr * pr - pi * pi; pi = 2.f * pr * pi; pr = t2; }
.LBB0_585:
	v_mov_b32_e32 v158, v48
	v_mov_b32_e32 v159, v49
	s_add_u32 s58, s58, 0x8000
	s_addc_u32 s59, s59, 0
	s_cmp_eq_u32 s58, 0x200000
	s_waitcnt vmcnt(0)
	v_cndmask_b32_e64 v53, v151, 0, s[4:5]
	v_cndmask_b32_e64 v52, v150, 0, s[4:5]
	v_cndmask_b32_e64 v51, v149, 0, s[4:5]
	v_cndmask_b32_e64 v50, v148, 0, s[4:5]
	v_lshl_add_u64 v[156:157], v[96:97], 0, s[58:59]
	global_load_dwordx4 v[148:151], v[156:157], off
	s_nop 1
	v_mfma_f32_16x16x32_bf16 v[54:57], v[50:53], v[0:3], 0
	v_mfma_f32_16x16x32_bf16 v[58:61], v[50:53], v[4:7], 0
	v_mfma_f32_16x16x32_bf16 v[62:65], v[50:53], v[8:11], 0
	v_mfma_f32_16x16x32_bf16 v[66:69], v[50:53], v[16:19], 0
	v_mfma_f32_16x16x32_bf16 v[70:73], v[50:53], v[12:15], 0
	v_mfma_f32_16x16x32_bf16 v[74:77], v[50:53], v[20:23], 0
	v_mfma_f32_16x16x32_bf16 v[100:103], v[50:53], v[24:27], 0
	v_mfma_f32_16x16x32_bf16 v[48:51], v[50:53], v[28:31], 0
	s_nop 1
	ds_write2_b32 v124, v54, v58 offset1:16
	ds_write2_b32 v124, v55, v59 offset0:132 offset1:148
	ds_write2_b32 v125, v56, v60 offset0:8 offset1:24
	ds_write2_b32 v125, v57, v61 offset0:140 offset1:156
	ds_write2_b32 v124, v62, v66 offset0:32 offset1:48
	ds_write2_b32 v124, v63, v67 offset0:164 offset1:180
	ds_write2_b32 v125, v64, v68 offset0:40 offset1:56
	ds_write2_b32 v125, v65, v69 offset0:172 offset1:188
	ds_write2_b32 v124, v70, v74 offset0:64 offset1:80
	ds_write2_b32 v124, v71, v75 offset0:196 offset1:212
	ds_write2_b32 v125, v72, v76 offset0:72 offset1:88
	ds_write2_b32 v125, v73, v77 offset0:204 offset1:220
	ds_write2_b32 v124, v100, v48 offset0:96 offset1:112
	ds_write2_b32 v124, v101, v49 offset0:228 offset1:244
	ds_write2_b32 v125, v102, v50 offset0:104 offset1:120
	ds_write2_b32 v125, v103, v51 offset0:236 offset1:252
	s_waitcnt lgkmcnt(0)
	ds_read2st64_b32 v[48:49], v111 offset0:16 offset1:17
	ds_read2st64_b32 v[50:51], v126 offset0:18 offset1:19
	ds_read2st64_b32 v[52:53], v127 offset0:20 offset1:21
	ds_read2st64_b32 v[54:55], v128 offset0:22 offset1:23
	ds_read2st64_b32 v[56:57], v129 offset0:24 offset1:25
	ds_read2st64_b32 v[58:59], v130 offset0:26 offset1:27
	ds_read2st64_b32 v[60:61], v131 offset0:28 offset1:29
	ds_read2st64_b32 v[62:63], v132 offset0:30 offset1:31
	ds_read2st64_b32 v[64:65], v133 offset0:32 offset1:33
	ds_read2st64_b32 v[66:67], v134 offset0:34 offset1:35
	ds_read2st64_b32 v[68:69], v135 offset0:36 offset1:37
	ds_read2st64_b32 v[70:71], v136 offset0:38 offset1:39
	ds_read2st64_b32 v[72:73], v137 offset0:40 offset1:41
	ds_read2st64_b32 v[74:75], v138 offset0:42 offset1:43
	ds_read2st64_b32 v[76:77], v139 offset0:44 offset1:45
	ds_read2st64_b32 v[78:79], v140 offset0:46 offset1:47
	s_waitcnt lgkmcnt(15)
	v_fma_f32 v160, v94, v158, v48
	v_fma_f32 v161, v94, v159, v49
	v_fma_f32 v162, -v95, v159, v160
	v_fma_f32 v163, v95, v158, v161
	s_waitcnt lgkmcnt(14)
	v_fma_f32 v160, v94, v162, v50
	v_fma_f32 v161, v94, v163, v51
	v_fma_f32 v158, -v95, v163, v160
	v_fma_f32 v159, v95, v162, v161
	s_waitcnt lgkmcnt(13)
	v_fma_f32 v160, v94, v158, v52
	v_fma_f32 v161, v94, v159, v53
	v_fma_f32 v162, -v95, v159, v160
	v_fma_f32 v163, v95, v158, v161
	s_waitcnt lgkmcnt(12)
	v_fma_f32 v160, v94, v162, v54
	v_fma_f32 v161, v94, v163, v55
	v_fma_f32 v158, -v95, v163, v160
	v_fma_f32 v159, v95, v162, v161
	s_waitcnt lgkmcnt(11)
	v_fma_f32 v160, v94, v158, v56
	v_fma_f32 v161, v94, v159, v57
	v_fma_f32 v162, -v95, v159, v160
	v_fma_f32 v163, v95, v158, v161
	s_waitcnt lgkmcnt(10)
	v_fma_f32 v160, v94, v162, v58
	v_fma_f32 v161, v94, v163, v59
	v_fma_f32 v158, -v95, v163, v160
	v_fma_f32 v159, v95, v162, v161
	s_waitcnt lgkmcnt(9)
	v_fma_f32 v160, v94, v158, v60
	v_fma_f32 v161, v94, v159, v61
	v_fma_f32 v162, -v95, v159, v160
	v_fma_f32 v163, v95, v158, v161
	s_waitcnt lgkmcnt(8)
	v_fma_f32 v160, v94, v162, v62
	v_fma_f32 v161, v94, v163, v63
	v_fma_f32 v158, -v95, v163, v160
	v_fma_f32 v159, v95, v162, v161
	s_waitcnt lgkmcnt(7)
	v_fma_f32 v160, v94, v158, v64
	v_fma_f32 v161, v94, v159, v65
	v_fma_f32 v162, -v95, v159, v160
	v_fma_f32 v163, v95, v158, v161
	s_waitcnt lgkmcnt(6)
	v_fma_f32 v160, v94, v162, v66
	v_fma_f32 v161, v94, v163, v67
	v_fma_f32 v158, -v95, v163, v160
	v_fma_f32 v159, v95, v162, v161
	s_waitcnt lgkmcnt(5)
	v_fma_f32 v160, v94, v158, v68
	v_fma_f32 v161, v94, v159, v69
	v_fma_f32 v162, -v95, v159, v160
	v_fma_f32 v163, v95, v158, v161
	s_waitcnt lgkmcnt(4)
	v_fma_f32 v160, v94, v162, v70
	v_fma_f32 v161, v94, v163, v71
	v_fma_f32 v158, -v95, v163, v160
	v_fma_f32 v159, v95, v162, v161
	s_waitcnt lgkmcnt(3)
	v_fma_f32 v160, v94, v158, v72
	v_fma_f32 v161, v94, v159, v73
	v_fma_f32 v162, -v95, v159, v160
	v_fma_f32 v163, v95, v158, v161
	s_waitcnt lgkmcnt(2)
	v_fma_f32 v160, v94, v162, v74
	v_fma_f32 v161, v94, v163, v75
	v_fma_f32 v158, -v95, v163, v160
	v_fma_f32 v159, v95, v162, v161
	s_waitcnt lgkmcnt(1)
	v_fma_f32 v160, v94, v158, v76
	v_fma_f32 v161, v94, v159, v77
	v_fma_f32 v162, -v95, v159, v160
	v_fma_f32 v163, v95, v158, v161
	s_waitcnt lgkmcnt(0)
	v_fma_f32 v160, v94, v162, v78
	v_fma_f32 v161, v94, v163, v79
	v_fma_f32 v48, -v95, v163, v160
	v_fma_f32 v49, v95, v162, v161
	s_cbranch_scc0 .LBB0_585
	s_andn2_b64 vcc, exec, s[8:9]
	ds_write_b64 v107, v[48:49]
	s_waitcnt lgkmcnt(0)
	s_barrier
	s_cbranch_vccnz .LBB0_591
	v_pk_mul_f32 v[48:49], v[94:95], v[94:95]
	s_andn2_b64 vcc, exec, s[18:19]
	v_sub_f32_e32 v48, v48, v49
	v_add_f32_e32 v49, v94, v94
	v_mul_f32_e32 v49, v95, v49
	v_mul_f32_e32 v50, v48, v48
	v_add_f32_e32 v48, v48, v48
	v_mul_f32_e32 v48, v49, v48
	v_fma_f32 v50, -v49, v49, v50
	v_mul_f32_e32 v49, v48, v48
	v_fma_f32 v49, v50, v50, -v49
	v_add_f32_e32 v50, v50, v50
	v_mul_f32_e32 v48, v48, v50
	v_mul_f32_e32 v50, v48, v48
	v_fma_f32 v50, v49, v49, -v50
	v_add_f32_e32 v49, v49, v49
	v_mul_f32_e32 v48, v48, v49
	v_mul_f32_e32 v49, v48, v48
	v_fma_f32 v49, v50, v50, -v49
	v_add_f32_e32 v50, v50, v50
	v_mul_f32_e32 v48, v48, v50
	v_mul_f32_e32 v50, v48, v48
	v_fma_f32 v50, v49, v49, -v50
	v_add_f32_e32 v49, v49, v49
	v_mul_f32_e32 v48, v48, v49
	v_mul_f32_e32 v49, v48, v48
	v_fma_f32 v49, v50, v50, -v49
	v_add_f32_e32 v50, v50, v50
	v_mul_f32_e32 v48, v48, v50
	v_mul_f32_e32 v50, v48, v48
	v_fma_f32 v50, v49, v49, -v50
	v_add_f32_e32 v49, v49, v49
	v_mul_f32_e32 v48, v48, v49
	v_mul_f32_e32 v49, v48, v48
	v_fma_f32 v49, v50, v50, -v49
	v_add_f32_e32 v50, v50, v50
	v_mul_f32_e32 v50, v48, v50
	v_mul_f32_e32 v48, v50, v50
	v_fma_f32 v48, v49, v49, -v48
	v_add_f32_e32 v49, v49, v49
	v_mul_f32_e32 v50, v50, v49
	s_cbranch_vccnz .LBB0_592
	v_mov_b32_e32 v76, 0
	v_mov_b32_e32 v49, v48
	v_mov_b32_e32 v51, v50
	s_mov_b32 s15, 0
	v_mov_b32_e32 v52, v108
	v_mov_b32_e32 v77, v76
